# transposes tiles also moved into layer 1's idle blocks (in-proj third round 216 x 16, top-k 480 x 4); P0b now covers tiles below 28592
# speedup vs baseline: 1.0077x; 1.0077x over previous
; __device__ __forceinline__ TrJob tr_decode(const Params& p, char* ws, int job) {
;   TrJob t;
;   int l = job / TJ_PER_LAYER, rj = job % TJ_PER_LAYER;
;   if (rj < 640) {
;     t.src = p.w_in + (size_t)l * 1024 * 2560; t.K = 1024; t.N = 2560; t.kt = rj / 40; t.nt = rj % 40;
;     t.dst = (u16*)(ws + OFF_WINT) + (size_t)l * 2560 * 1024; t.mode = 0;
;   } else if (rj < 896) {
;     rj -= 640;
;     t.src = p.w_out + (size_t)l * 1024 * 1024; t.K = 1024; t.N = 1024; t.kt = rj / 16; t.nt = rj % 16;
;     t.dst = (u16*)(ws + OFF_WOUTT) + (size_t)l * 1024 * 1024; t.mode = 0;
;   } else {
;     rj -= 896;
;     int e = rj / 1536, q = rj % 1536;
;     size_t eo = (size_t)(l * 16 + e);
;     if (q < 512) {
;       t.src = p.w_gate + eo * 1024 * 2048; t.K = 1024; t.N = 2048; t.kt = q / 32; t.nt = q % 32;
;       t.dst = (u16*)(ws + OFF_WGUT) + eo * 4096 * 1024; t.mode = 1;
;     } else if (q < 1024) {
;       q -= 512;
;       t.src = p.w_up + eo * 1024 * 2048; t.K = 1024; t.N = 2048; t.kt = q / 32; t.nt = q % 32;
;       t.dst = (u16*)(ws + OFF_WGUT) + eo * 4096 * 1024; t.mode = 2;
;     } else {
;       q -= 1024;
;       t.src = p.w_down + eo * 2048 * 1024; t.K = 2048; t.N = 1024; t.kt = q / 16; t.nt = q % 16;
;       t.dst = (u16*)(ws + OFF_WDT) + eo * 1024 * 2048; t.mode = 0;
;     }
;   }
; __device__ __forceinline__ void p0_transposes(const Params& p, char* smem, int bid, int nb, int jlo, int jhi) {
;     ...
;   for (; j < jhi; j += 2 * nb) {
;     const int jn = j + 2 * nb;
;     if (jn < jhi) { tr_load(p, ws, jn, tid, n0); tr_load(p, ws, jn + 1, tid, n1); }
.LBB0_174:
	s_add_i32 s96, s97, s75
	s_cmp_gt_i32 s96, 0x6faf
	s_cselect_b64 s[0:1], -1, 0
	s_and_b64 vcc, exec, s[0:1]
	s_cbranch_vccnz .LBB0_208
	s_mul_hi_i32 s10, s96, 0x5254e78f
	s_lshr_b32 s11, s10, 31
	s_ashr_i32 s10, s10, 13
	s_add_i32 s52, s10, s11
	s_mul_i32 s10, s52, 0xffff9c80
	s_add_i32 s10, s96, s10
	s_cmpk_gt_i32 s10, 0x27f
	s_mov_b64 s[58:59], -1
	s_cbranch_scc0 .LBB0_189
	s_cmpk_gt_u32 s10, 0x37f
	s_cbranch_scc0 .LBB0_186
	s_add_i32 s11, s10, 0xfc80
	s_and_b32 s33, s11, 0xffff
	s_mul_i32 s33, s33, 0xaaab
	s_lshr_b32 s33, s33, 26
	s_mul_i32 s40, s33, 0x600
	s_sub_i32 s11, s11, s40
	s_and_b32 s40, s11, 0xffff
	s_lshl_b32 s11, s52, 4
	s_add_i32 s54, s11, s33
	s_ashr_i32 s55, s54, 31
	s_lshl_b64 s[58:59], s[54:55], 23
	s_cmpk_gt_u32 s40, 0x1ff
	s_mov_b64 s[60:61], -1
	s_cbranch_scc0 .LBB0_183
	s_cmpk_gt_u32 s40, 0x3ff
	s_mov_b64 s[56:57], -1
	s_cbranch_scc0 .LBB0_180
	v_readlane_b32 s12, v238, 25
	s_add_i32 s11, s40, 0xfffffc00
	v_readlane_b32 s18, v238, 31
	v_readlane_b32 s19, v238, 32
	s_add_u32 s54, s18, s58
	v_readlane_b32 s13, v238, 26
	v_readlane_b32 s14, v238, 27
	v_readlane_b32 s15, v238, 28
	v_readlane_b32 s16, v238, 29
	v_readlane_b32 s17, v238, 30
	s_addc_u32 s55, s19, s59
	s_lshr_b32 s33, s11, 4
	s_and_b32 s11, s40, 15
	s_mov_b64 s[56:57], 0

; #define GSYNC() do { xcd_barrier(xb); if (REP_MASK & 256) xcd_barrier(xb); } while (0)
; #define LAUNDER(v) asm volatile("" : "+s"(v))
; __device__ __forceinline__ int vtid() { int t = threadIdx.x; asm volatile("" : "+v"(t)); return t; }
; __device__ __forceinline__ void p0_transposes(const Params& p, char* smem, int bid, int nb, int jlo, int jhi) {
;   const int tid = vtid();
;   char* ws = p.ws;
;   LAUNDER(ws);
;   float* tileA = (float*)smem;
;   float* tileB = tileA + 64 * 65;
;   float4 c0[4], c1[4], n0[4], n1[4];
;   int j = jlo + bid * 2;
;   if (j < jhi) { tr_load(p, ws, j, tid, c0); tr_load(p, ws, j + 1, tid, c1); }
;   for (; j < jhi; j += 2 * nb) {
; __global__ void __launch_bounds__(256, 2) fwd_megakernel(Params p) {
;     ...
;   for (int l = 0; l < 2; ++l) {
;     for (int rep = 0; rep < NREP(1); ++rep) {
;       for (int t = bid; t < 66 * 20; t += nb) inproj_tile(p, smem, l, t / 20, t % 20);
;       GSYNC();
.Ltrp1_check:
	v_readlane_b32 s0, v239, 0
	s_cmpk_lt_i32 s0, 296
	s_cbranch_scc1 .LBB0_631
	v_readlane_b32 s100, v236, 62
	v_readlane_b32 s101, v236, 63
	v_writelane_b32 v255, s64, 0
	v_writelane_b32 v255, s65, 1
	v_writelane_b32 v255, s66, 2
	v_writelane_b32 v255, s67, 3
	v_writelane_b32 v255, s68, 4
	v_writelane_b32 v255, s69, 5
	v_writelane_b32 v255, s70, 6
	v_writelane_b32 v255, s71, 7
	v_writelane_b32 v255, s72, 8
	v_writelane_b32 v255, s73, 9
	v_writelane_b32 v255, s74, 10
	v_writelane_b32 v255, s75, 11
	v_writelane_b32 v255, s76, 12
	v_writelane_b32 v255, s77, 13
	v_writelane_b32 v255, s78, 14
	v_writelane_b32 v255, s79, 15
	v_writelane_b32 v255, s80, 16
	v_writelane_b32 v255, s81, 17
	v_writelane_b32 v255, s82, 18
	v_writelane_b32 v255, s83, 19
	v_writelane_b32 v255, s84, 20
	v_writelane_b32 v255, s85, 21
	v_writelane_b32 v255, s86, 22
	v_writelane_b32 v255, s87, 23
	v_writelane_b32 v255, s88, 24
	v_writelane_b32 v255, s89, 25
	v_writelane_b32 v255, s90, 26
	v_writelane_b32 v255, s91, 27
	v_writelane_b32 v255, s92, 28
	v_writelane_b32 v255, s93, 29
	v_writelane_b32 v255, s94, 30
	v_writelane_b32 v255, s95, 31
	v_writelane_b32 v255, s96, 32
	v_writelane_b32 v255, s97, 33
	v_writelane_b32 v255, s98, 34
	v_writelane_b32 v255, s99, 35
	v_writelane_b32 v255, vcc_lo, 36
	v_writelane_b32 v255, vcc_hi, 37
	s_load_dwordx4 s[64:67], s[100:101], 0x40
	s_load_dwordx4 s[68:71], s[100:101], 0xc8
	s_load_dwordx2 s[72:73], s[100:101], 0xd8
	s_load_dwordx2 s[74:75], s[100:101], 0xe8
	v_and_b32_e32 v241, 15, v172
	v_lshrrev_b32_e32 v242, 4, v172
	v_lshlrev_b32_e32 v241, 4, v241
	v_mul_u32_u24_e32 v243, 0x104, v242
	v_add_u32_e32 v243, v243, v241
	v_and_b32_e32 v246, 7, v172
	v_lshrrev_b32_e32 v245, 3, v172
	v_mul_u32_u24_e32 v244, 0x820, v246
	v_lshl_add_u32 v244, v245, 2, v244
	v_lshlrev_b32_e32 v246, 4, v246
	v_readlane_b32 s79, v237, 29
	s_mov_b32 s77, 36952
	s_mov_b32 s78, 30216
	s_cmp_lg_u32 s79, 0
	s_cselect_b32 s77, s77, s78
	v_readlane_b32 s76, v239, 0
	s_add_u32 s76, s76, s77
	s_movk_i32 s77, 8
	s_mov_b32 s96, 0
	s_waitcnt lgkmcnt(0)

; #define LAUNDER(v) asm volatile("" : "+s"(v))
; __device__ __forceinline__ int vtid() { int t = threadIdx.x; asm volatile("" : "+v"(t)); return t; }
; __device__ __forceinline__ unsigned pack2(float a, float b) { return (unsigned)f2bf(a) | ((unsigned)f2bf(b) << 16); }
; __device__ __forceinline__ void tr_store(const Params& p, char* ws, int job, int tid, const float* tile) {
;   TrJob t = tr_decode(p, ws, job);
;   const int kc = tid & 7, nn = tid >> 3;
; #pragma unroll
;   for (int pp = 0; pp < 2; ++pp) {
;     int n = nn + 32 * pp;
;     float v[8];
; #pragma unroll
;     for (int j = 0; j < 8; ++j) v[j] = tile[(kc * 8 + j) * 65 + n];
;     uint4 o;
;     o.x = pack2(v[0], v[1]); o.y = pack2(v[2], v[3]); o.z = pack2(v[4], v[5]); o.w = pack2(v[6], v[7]);
;     int gn = t.nt * 64 + n;
;     int drow = t.mode == 0 ? gn : gu_row(t.mode - 1, gn);
;     *(uint4*)&t.dst[(size_t)drow * t.K + t.kt * 64 + kc * 8] = o;
;   }
; }
; __device__ __forceinline__ void p0_transposes(const Params& p, char* smem, int bid, int nb, int jlo, int jhi) {
;   const int tid = vtid();
;   char* ws = p.ws;
;   LAUNDER(ws);
;   float* tileA = (float*)smem;
;   float* tileB = tileA + 64 * 65;
;   float4 c0[4], c1[4], n0[4], n1[4];
;   int j = jlo + bid * 2;
;   if (j < jhi) { tr_load(p, ws, j, tid, c0); tr_load(p, ws, j + 1, tid, c1); }
;   for (; j < jhi; j += 2 * nb) {
;     const int jn = j + 2 * nb;
;     if (jn < jhi) { tr_load(p, ws, jn, tid, n0); tr_load(p, ws, jn + 1, tid, n1); }
;     tr_lds_write(tileA, tid, c0);
;     tr_lds_write(tileB, tid, c1);
;     __syncthreads();
;     tr_store(p, ws, j, tid, tileA);
;     tr_store(p, ws, j + 1, tid, tileB);
;     __syncthreads();
; #pragma unroll
;     for (int q = 0; q < 4; ++q) { c0[q] = n0[q]; c1[q] = n1[q]; }
;   }
.Ltr_p5as1_dec_done:
	s_lshl_b32 s97, s83, 1
	s_cmp_eq_u32 s84, -1
	s_cselect_b32 s79, 6, 7
	s_cselect_b32 s85, 32, 64
	s_cselect_b32 s78, 0, s84
	s_lshl_b32 s79, s81, s79
	s_add_u32 s79, s79, s78
	s_add_u32 s85, s85, s79
	s_mul_i32 s79, s79, s97
	s_mul_i32 s85, s85, s97
	s_lshl_b32 s78, s80, 7
	s_add_u32 s79, s79, s78
	s_add_u32 s85, s85, s78
	s_add_u32 s94, s88, s79
	s_addc_u32 s95, s89, 0
	s_add_u32 s98, s88, s85
	s_addc_u32 s99, s89, 0
	v_mad_u32_u24 v254, v245, s97, v246
	s_movk_i32 s78, 0x7fff
	s_mov_b32 s79, 0xffff0000
	s_waitcnt lgkmcnt(0)
	v_bfe_u32 v252, v228, 16, 1
	v_bfe_u32 v253, v229, 16, 1
	v_add3_u32 v252, v228, v252, s78
	v_add3_u32 v253, v229, v253, s78
	v_lshrrev_b32_e32 v252, 16, v252
	v_and_or_b32 v248, v253, s79, v252
	v_bfe_u32 v252, v230, 16, 1
	v_bfe_u32 v253, v231, 16, 1
	v_add3_u32 v252, v230, v252, s78
	v_add3_u32 v253, v231, v253, s78
	v_lshrrev_b32_e32 v252, 16, v252
	v_and_or_b32 v249, v253, s79, v252
	v_bfe_u32 v252, v232, 16, 1
	v_bfe_u32 v253, v233, 16, 1
	v_add3_u32 v252, v232, v252, s78
	v_add3_u32 v253, v233, v253, s78
	v_lshrrev_b32_e32 v252, 16, v252
	v_and_or_b32 v250, v253, s79, v252
	v_bfe_u32 v252, v234, 16, 1
	v_bfe_u32 v253, v235, 16, 1
	v_add3_u32 v252, v234, v252, s78
	v_add3_u32 v253, v235, v253, s78
	v_lshrrev_b32_e32 v252, 16, v252
	v_and_or_b32 v251, v253, s79, v252
	global_store_dwordx4 v254, v[248:251], s[94:95]
	s_nop 1
	v_bfe_u32 v252, v186, 16, 1
	v_bfe_u32 v253, v187, 16, 1
	v_add3_u32 v252, v186, v252, s78
	v_add3_u32 v253, v187, v253, s78
	v_lshrrev_b32_e32 v252, 16, v252
	v_and_or_b32 v248, v253, s79, v252
	v_bfe_u32 v252, v188, 16, 1
	v_bfe_u32 v253, v189, 16, 1
	v_add3_u32 v252, v188, v252, s78
	v_add3_u32 v253, v189, v253, s78
	v_lshrrev_b32_e32 v252, 16, v252
	v_and_or_b32 v249, v253, s79, v252
	v_bfe_u32 v252, v190, 16, 1
	v_bfe_u32 v253, v191, 16, 1
	v_add3_u32 v252, v190, v252, s78
	v_add3_u32 v253, v191, v253, s78
	v_lshrrev_b32_e32 v252, 16, v252
	v_and_or_b32 v250, v253, s79, v252
	v_bfe_u32 v252, v192, 16, 1
	v_bfe_u32 v253, v193, 16, 1
	v_add3_u32 v252, v192, v252, s78
	v_add3_u32 v253, v193, v253, s78
	v_lshrrev_b32_e32 v252, 16, v252
	v_and_or_b32 v251, v253, s79, v252
	global_store_dwordx4 v254, v[248:251], s[98:99]
	s_xor_b32 s96, s96, 0x4100
	s_add_u32 s76, s76, 448
	s_sub_u32 s77, s77, 1
	s_cmp_lg_u32 s77, 0
	s_cbranch_scc1 .Ltrp5a_batch
	s_waitcnt vmcnt(0) lgkmcnt(0)
	s_barrier
	v_readlane_b32 s64, v255, 0
	v_readlane_b32 s65, v255, 1
	v_readlane_b32 s66, v255, 2
	v_readlane_b32 s67, v255, 3
	v_readlane_b32 s68, v255, 4
	v_readlane_b32 s69, v255, 5
	v_readlane_b32 s70, v255, 6
	v_readlane_b32 s71, v255, 7
	v_readlane_b32 s72, v255, 8
	v_readlane_b32 s73, v255, 9
	v_readlane_b32 s74, v255, 10
	v_readlane_b32 s75, v255, 11
	v_readlane_b32 s76, v255, 12
	v_readlane_b32 s77, v255, 13
	v_readlane_b32 s78, v255, 14
	v_readlane_b32 s79, v255, 15
	v_readlane_b32 s80, v255, 16
	v_readlane_b32 s81, v255, 17
	v_readlane_b32 s82, v255, 18
	v_readlane_b32 s83, v255, 19
	v_readlane_b32 s84, v255, 20
	v_readlane_b32 s85, v255, 21
	v_readlane_b32 s86, v255, 22
	v_readlane_b32 s87, v255, 23
	v_readlane_b32 s88, v255, 24
	v_readlane_b32 s89, v255, 25
	v_readlane_b32 s90, v255, 26
	v_readlane_b32 s91, v255, 27
	v_readlane_b32 s92, v255, 28
	v_readlane_b32 s93, v255, 29
	v_readlane_b32 s94, v255, 30
	v_readlane_b32 s95, v255, 31
	v_readlane_b32 s96, v255, 32
	v_readlane_b32 s97, v255, 33
	v_readlane_b32 s98, v255, 34
	v_readlane_b32 s99, v255, 35
	v_readlane_b32 vcc_lo, v255, 36
	v_readlane_b32 vcc_hi, v255, 37
	s_nop 4
	s_branch .LBB0_1324
.Ltrp5_l1:
	v_readlane_b32 s100, v236, 62
	v_readlane_b32 s101, v236, 63
	v_writelane_b32 v255, s64, 0
	v_writelane_b32 v255, s65, 1
	v_writelane_b32 v255, s66, 2
	v_writelane_b32 v255, s67, 3
	v_writelane_b32 v255, s68, 4
	v_writelane_b32 v255, s69, 5
	v_writelane_b32 v255, s70, 6
	v_writelane_b32 v255, s71, 7
	v_writelane_b32 v255, s72, 8
	v_writelane_b32 v255, s73, 9
	v_writelane_b32 v255, s74, 10
	v_writelane_b32 v255, s75, 11
	v_writelane_b32 v255, s76, 12
	v_writelane_b32 v255, s77, 13
	v_writelane_b32 v255, s78, 14
	v_writelane_b32 v255, s79, 15
	v_writelane_b32 v255, s80, 16
	v_writelane_b32 v255, s81, 17
	v_writelane_b32 v255, s82, 18
	v_writelane_b32 v255, s83, 19
	v_writelane_b32 v255, s84, 20
	v_writelane_b32 v255, s85, 21
	v_writelane_b32 v255, s86, 22
	v_writelane_b32 v255, s87, 23
	v_writelane_b32 v255, s88, 24
	v_writelane_b32 v255, s89, 25
	v_writelane_b32 v255, s90, 26
	v_writelane_b32 v255, s91, 27
	v_writelane_b32 v255, s92, 28
	v_writelane_b32 v255, s93, 29
	v_writelane_b32 v255, s94, 30
	v_writelane_b32 v255, s95, 31
	v_writelane_b32 v255, s96, 32
	v_writelane_b32 v255, s97, 33
	v_writelane_b32 v255, s98, 34
	v_writelane_b32 v255, s99, 35
	v_writelane_b32 v255, vcc_lo, 36
	v_writelane_b32 v255, vcc_hi, 37
	s_load_dwordx4 s[64:67], s[100:101], 0x40
	s_load_dwordx4 s[68:71], s[100:101], 0xc8
	s_load_dwordx2 s[72:73], s[100:101], 0xd8
	s_load_dwordx2 s[74:75], s[100:101], 0xe8
	v_and_b32_e32 v241, 15, v172
	v_lshrrev_b32_e32 v242, 4, v172
	v_lshlrev_b32_e32 v241, 4, v241
	v_mul_u32_u24_e32 v243, 0x104, v242
	v_add_u32_e32 v243, v243, v241
	v_and_b32_e32 v246, 7, v172
	v_lshrrev_b32_e32 v245, 3, v172
	v_mul_u32_u24_e32 v244, 0x820, v246
	v_lshl_add_u32 v244, v245, 2, v244
	v_lshlrev_b32_e32 v246, 4, v246
	v_readlane_b32 s76, v239, 0
	s_add_u32 s76, s76, 28560
	s_movk_i32 s77, 2
	s_mov_b32 s96, 0
	s_waitcnt lgkmcnt(0)
.Ltrp5b_batch:
	s_min_u32 s78, s76, 30511
	s_cmp_ge_u32 s78, 25472
	s_cselect_b32 s79, 1, 0
	s_cselect_b32 s85, 25472, 0
	s_sub_u32 s78, s78, s85
	s_cmp_lt_u32 s78, 640
	s_cbranch_scc0 .Ltr_p5bl0_notin
	s_mul_hi_u32 s80, s78, 107374183
	s_mul_i32 s85, s80, 40
	s_sub_u32 s81, s78, s85
	s_movk_i32 s82, 2560
	s_movk_i32 s83, 1024
	s_mov_b32 s84, -1
	s_mul_i32 s85, s79, 10485760
	s_add_u32 s86, s64, s85
	s_addc_u32 s87, s65, 0
	s_mul_i32 s85, s79, 5242880
	s_add_u32 s88, s74, s85
	s_addc_u32 s89, s75, 0
	s_branch .Ltr_p5bl0_dec_done

; __device__ __forceinline__ TrJob tr_decode(const Params& p, char* ws, int job) {
;   TrJob t;
;   int l = job / TJ_PER_LAYER, rj = job % TJ_PER_LAYER;
;   if (rj < 640) {
;     t.src = p.w_in + (size_t)l * 1024 * 2560; t.K = 1024; t.N = 2560; t.kt = rj / 40; t.nt = rj % 40;
;     t.dst = (u16*)(ws + OFF_WINT) + (size_t)l * 2560 * 1024; t.mode = 0;
; __device__ __forceinline__ void tr_load(const Params& p, char* ws, int job, int tid, float4 (&r)[4]) {
;   TrJob t = tr_decode(p, ws, job);
;   const int c4 = tid & 15, rr = tid >> 4;
;   const float* s0 = t.src + (size_t)(t.kt * 64 + rr) * t.N + t.nt * 64 + c4 * 4;
; #pragma unroll
;   for (int pp = 0; pp < 4; ++pp) {
;     f32x4 v_ = __builtin_nontemporal_load((const f32x4*)(s0 + (size_t)(16 * pp) * t.N));
;     r[pp] = make_float4(v_[0], v_[1], v_[2], v_[3]);
;   }
; }
.Ltr_p5bl0_dec_done:
	s_mul_i32 s85, s80, s82
	s_lshl_b32 s85, s85, 8
	s_lshl_b32 s79, s81, 8
	s_add_u32 s85, s85, s79
	s_add_u32 s90, s86, s85
	s_addc_u32 s91, s87, 0
	s_lshl_b32 s92, s82, 2
	s_lshl_b32 s93, s82, 6
	v_mad_u32_u24 v240, v242, s92, v241
	global_load_dwordx4 v[212:215], v240, s[90:91] nt
	v_add_u32_e32 v211, s93, v240
	global_load_dwordx4 v[216:219], v211, s[90:91] nt
	v_add_u32_e32 v240, s93, v211
	global_load_dwordx4 v[220:223], v240, s[90:91] nt
	v_add_u32_e32 v211, s93, v240
	global_load_dwordx4 v[224:227], v211, s[90:91] nt
	s_add_u32 s76, s76, 480
	s_min_u32 s78, s76, 30511
	s_cmp_ge_u32 s78, 25472
	s_cselect_b32 s79, 1, 0
	s_cselect_b32 s85, 25472, 0
	s_sub_u32 s78, s78, s85
	s_cmp_lt_u32 s78, 640
	s_cbranch_scc0 .Ltr_p5bl1_notin
	s_mul_hi_u32 s80, s78, 107374183
	s_mul_i32 s85, s80, 40
	s_sub_u32 s81, s78, s85
	s_movk_i32 s82, 2560
	s_movk_i32 s83, 1024
	s_mov_b32 s84, -1
	s_mul_i32 s85, s79, 10485760
	s_add_u32 s86, s64, s85
	s_addc_u32 s87, s65, 0
	s_mul_i32 s85, s79, 5242880
	s_add_u32 s88, s74, s85
	s_addc_u32 s89, s75, 0
	s_branch .Ltr_p5bl1_dec_done

; __device__ __forceinline__ void tr_load(const Params& p, char* ws, int job, int tid, float4 (&r)[4]) {
;   TrJob t = tr_decode(p, ws, job);
;   const int c4 = tid & 15, rr = tid >> 4;
;   const float* s0 = t.src + (size_t)(t.kt * 64 + rr) * t.N + t.nt * 64 + c4 * 4;
; #pragma unroll
;   for (int pp = 0; pp < 4; ++pp) {
;     f32x4 v_ = __builtin_nontemporal_load((const f32x4*)(s0 + (size_t)(16 * pp) * t.N));
;     r[pp] = make_float4(v_[0], v_[1], v_[2], v_[3]);
;   }
; }
; __device__ __forceinline__ void tr_lds_write(float* tile, int tid, const float4 (&r)[4]) {
;   const int c4 = tid & 15, rr = tid >> 4;
; #pragma unroll
;   for (int pp = 0; pp < 4; ++pp) {
;     float* t = &tile[(rr + 16 * pp) * 65 + c4 * 4];
;     t[0] = r[pp].x; t[1] = r[pp].y; t[2] = r[pp].z; t[3] = r[pp].w;
;   }
; }
; __device__ __forceinline__ void tr_store(const Params& p, char* ws, int job, int tid, const float* tile) {
;   TrJob t = tr_decode(p, ws, job);
;   const int kc = tid & 7, nn = tid >> 3;
; #pragma unroll
;   for (int pp = 0; pp < 2; ++pp) {
;     int n = nn + 32 * pp;
;     float v[8];
; #pragma unroll
;     for (int j = 0; j < 8; ++j) v[j] = tile[(kc * 8 + j) * 65 + n];
.Ltr_p5bl1_dec_done:
	s_mul_i32 s85, s80, s82
	s_lshl_b32 s85, s85, 8
	s_lshl_b32 s79, s81, 8
	s_add_u32 s85, s85, s79
	s_add_u32 s90, s86, s85
	s_addc_u32 s91, s87, 0
	s_lshl_b32 s92, s82, 2
	s_lshl_b32 s93, s82, 6
	v_mad_u32_u24 v240, v242, s92, v241
	global_load_dwordx4 v[228:231], v240, s[90:91] nt
	v_add_u32_e32 v211, s93, v240
	global_load_dwordx4 v[232:235], v211, s[90:91] nt
	v_add_u32_e32 v240, s93, v211
	global_load_dwordx4 v[186:189], v240, s[90:91] nt
	v_add_u32_e32 v211, s93, v240
	global_load_dwordx4 v[190:193], v211, s[90:91] nt
	s_add_u32 s76, s76, 480
	s_sub_u32 s76, s76, 960
	s_waitcnt vmcnt(0)
	v_add_u32_e32 v247, s96, v243
	ds_write_b32 v247, v212 offset:0
	ds_write_b32 v247, v213 offset:4
	ds_write_b32 v247, v214 offset:8
	ds_write_b32 v247, v215 offset:12
	ds_write_b32 v247, v216 offset:4160
	ds_write_b32 v247, v217 offset:4164
	ds_write_b32 v247, v218 offset:4168
	ds_write_b32 v247, v219 offset:4172
	ds_write_b32 v247, v220 offset:8320
	ds_write_b32 v247, v221 offset:8324
	ds_write_b32 v247, v222 offset:8328
	ds_write_b32 v247, v223 offset:8332
	ds_write_b32 v247, v224 offset:12480
	ds_write_b32 v247, v225 offset:12484
	ds_write_b32 v247, v226 offset:12488
	ds_write_b32 v247, v227 offset:12492
	v_add_u32_e32 v247, s96, v244
	s_waitcnt lgkmcnt(0)
	s_barrier
	ds_read_b32 v212, v247 offset:0
	ds_read_b32 v213, v247 offset:260
	ds_read_b32 v214, v247 offset:520
	ds_read_b32 v215, v247 offset:780
	ds_read_b32 v216, v247 offset:1040
	ds_read_b32 v217, v247 offset:1300
	ds_read_b32 v218, v247 offset:1560
	ds_read_b32 v219, v247 offset:1820
	ds_read_b32 v220, v247 offset:128
	ds_read_b32 v221, v247 offset:388
	ds_read_b32 v222, v247 offset:648
	ds_read_b32 v223, v247 offset:908
	ds_read_b32 v224, v247 offset:1168
	ds_read_b32 v225, v247 offset:1428
	ds_read_b32 v226, v247 offset:1688
	ds_read_b32 v227, v247 offset:1948
	s_min_u32 s78, s76, 30511
	s_cmp_ge_u32 s78, 25472
	s_cselect_b32 s79, 1, 0
	s_cselect_b32 s85, 25472, 0
	s_sub_u32 s78, s78, s85
	s_cmp_lt_u32 s78, 640
	s_cbranch_scc0 .Ltr_p5bs0_notin
	s_mul_hi_u32 s80, s78, 107374183
	s_mul_i32 s85, s80, 40
	s_sub_u32 s81, s78, s85
	s_movk_i32 s82, 2560
	s_movk_i32 s83, 1024
	s_mov_b32 s84, -1
	s_mul_i32 s85, s79, 10485760
	s_add_u32 s86, s64, s85
	s_addc_u32 s87, s65, 0
	s_mul_i32 s85, s79, 5242880
	s_add_u32 s88, s74, s85
	s_addc_u32 s89, s75, 0
	s_branch .Ltr_p5bs0_dec_done

; __device__ __forceinline__ unsigned pack2(float a, float b) { return (unsigned)f2bf(a) | ((unsigned)f2bf(b) << 16); }
; __device__ __forceinline__ void tr_lds_write(float* tile, int tid, const float4 (&r)[4]) {
;   const int c4 = tid & 15, rr = tid >> 4;
; #pragma unroll
;   for (int pp = 0; pp < 4; ++pp) {
;     float* t = &tile[(rr + 16 * pp) * 65 + c4 * 4];
;     t[0] = r[pp].x; t[1] = r[pp].y; t[2] = r[pp].z; t[3] = r[pp].w;
;   }
; }
; __device__ __forceinline__ void tr_store(const Params& p, char* ws, int job, int tid, const float* tile) {
;   TrJob t = tr_decode(p, ws, job);
;   const int kc = tid & 7, nn = tid >> 3;
; #pragma unroll
;   for (int pp = 0; pp < 2; ++pp) {
;     int n = nn + 32 * pp;
;     float v[8];
; #pragma unroll
;     for (int j = 0; j < 8; ++j) v[j] = tile[(kc * 8 + j) * 65 + n];
;     uint4 o;
;     o.x = pack2(v[0], v[1]); o.y = pack2(v[2], v[3]); o.z = pack2(v[4], v[5]); o.w = pack2(v[6], v[7]);
;     int gn = t.nt * 64 + n;
;     int drow = t.mode == 0 ? gn : gu_row(t.mode - 1, gn);
;     *(uint4*)&t.dst[(size_t)drow * t.K + t.kt * 64 + kc * 8] = o;
;   }
; }
.Ltr_p5bs0_dec_done:
	s_lshl_b32 s97, s83, 1
	s_cmp_eq_u32 s84, -1
	s_cselect_b32 s79, 6, 7
	s_cselect_b32 s85, 32, 64
	s_cselect_b32 s78, 0, s84
	s_lshl_b32 s79, s81, s79
	s_add_u32 s79, s79, s78
	s_add_u32 s85, s85, s79
	s_mul_i32 s79, s79, s97
	s_mul_i32 s85, s85, s97
	s_lshl_b32 s78, s80, 7
	s_add_u32 s79, s79, s78
	s_add_u32 s85, s85, s78
	s_add_u32 s94, s88, s79
	s_addc_u32 s95, s89, 0
	s_add_u32 s98, s88, s85
	s_addc_u32 s99, s89, 0
	v_mad_u32_u24 v254, v245, s97, v246
	s_movk_i32 s78, 0x7fff
	s_mov_b32 s79, 0xffff0000
	s_waitcnt lgkmcnt(0)
	v_bfe_u32 v252, v212, 16, 1
	v_bfe_u32 v253, v213, 16, 1
	v_add3_u32 v252, v212, v252, s78
	v_add3_u32 v253, v213, v253, s78
	v_lshrrev_b32_e32 v252, 16, v252
	v_and_or_b32 v248, v253, s79, v252
	v_bfe_u32 v252, v214, 16, 1
	v_bfe_u32 v253, v215, 16, 1
	v_add3_u32 v252, v214, v252, s78
	v_add3_u32 v253, v215, v253, s78
	v_lshrrev_b32_e32 v252, 16, v252
	v_and_or_b32 v249, v253, s79, v252
	v_bfe_u32 v252, v216, 16, 1
	v_bfe_u32 v253, v217, 16, 1
	v_add3_u32 v252, v216, v252, s78
	v_add3_u32 v253, v217, v253, s78
	v_lshrrev_b32_e32 v252, 16, v252
	v_and_or_b32 v250, v253, s79, v252
	v_bfe_u32 v252, v218, 16, 1
	v_bfe_u32 v253, v219, 16, 1
	v_add3_u32 v252, v218, v252, s78
	v_add3_u32 v253, v219, v253, s78
	v_lshrrev_b32_e32 v252, 16, v252
	v_and_or_b32 v251, v253, s79, v252
	global_store_dwordx4 v254, v[248:251], s[94:95]
	s_nop 1
	v_bfe_u32 v252, v220, 16, 1
	v_bfe_u32 v253, v221, 16, 1
	v_add3_u32 v252, v220, v252, s78
	v_add3_u32 v253, v221, v253, s78
	v_lshrrev_b32_e32 v252, 16, v252
	v_and_or_b32 v248, v253, s79, v252
	v_bfe_u32 v252, v222, 16, 1
	v_bfe_u32 v253, v223, 16, 1
	v_add3_u32 v252, v222, v252, s78
	v_add3_u32 v253, v223, v253, s78
	v_lshrrev_b32_e32 v252, 16, v252
	v_and_or_b32 v249, v253, s79, v252
	v_bfe_u32 v252, v224, 16, 1
	v_bfe_u32 v253, v225, 16, 1
	v_add3_u32 v252, v224, v252, s78
	v_add3_u32 v253, v225, v253, s78
	v_lshrrev_b32_e32 v252, 16, v252
	v_and_or_b32 v250, v253, s79, v252
	v_bfe_u32 v252, v226, 16, 1
	v_bfe_u32 v253, v227, 16, 1
	v_add3_u32 v252, v226, v252, s78
	v_add3_u32 v253, v227, v253, s78
	v_lshrrev_b32_e32 v252, 16, v252
	v_and_or_b32 v251, v253, s79, v252
	global_store_dwordx4 v254, v[248:251], s[98:99]
	s_xor_b32 s96, s96, 0x4100
	s_add_u32 s76, s76, 480
	v_add_u32_e32 v247, s96, v243
	ds_write_b32 v247, v228 offset:0
	ds_write_b32 v247, v229 offset:4
	ds_write_b32 v247, v230 offset:8
	ds_write_b32 v247, v231 offset:12
	ds_write_b32 v247, v232 offset:4160
	ds_write_b32 v247, v233 offset:4164
	ds_write_b32 v247, v234 offset:4168
	ds_write_b32 v247, v235 offset:4172
	ds_write_b32 v247, v186 offset:8320
	ds_write_b32 v247, v187 offset:8324
	ds_write_b32 v247, v188 offset:8328
	ds_write_b32 v247, v189 offset:8332
	ds_write_b32 v247, v190 offset:12480
	ds_write_b32 v247, v191 offset:12484
	ds_write_b32 v247, v192 offset:12488
	ds_write_b32 v247, v193 offset:12492
	v_add_u32_e32 v247, s96, v244
	s_waitcnt lgkmcnt(0)
	s_barrier
	ds_read_b32 v228, v247 offset:0
	ds_read_b32 v229, v247 offset:260
	ds_read_b32 v230, v247 offset:520
	ds_read_b32 v231, v247 offset:780
	ds_read_b32 v232, v247 offset:1040
	ds_read_b32 v233, v247 offset:1300
	ds_read_b32 v234, v247 offset:1560
	ds_read_b32 v235, v247 offset:1820
	ds_read_b32 v186, v247 offset:128
	ds_read_b32 v187, v247 offset:388
	ds_read_b32 v188, v247 offset:648
	ds_read_b32 v189, v247 offset:908
	ds_read_b32 v190, v247 offset:1168
	ds_read_b32 v191, v247 offset:1428
	ds_read_b32 v192, v247 offset:1688
	ds_read_b32 v193, v247 offset:1948
	s_min_u32 s78, s76, 30511
	s_cmp_ge_u32 s78, 25472
	s_cselect_b32 s79, 1, 0
	s_cselect_b32 s85, 25472, 0
	s_sub_u32 s78, s78, s85
	s_cmp_lt_u32 s78, 640
	s_cbranch_scc0 .Ltr_p5bs1_notin
	s_mul_hi_u32 s80, s78, 107374183
	s_mul_i32 s85, s80, 40
	s_sub_u32 s81, s78, s85
	s_movk_i32 s82, 2560
	s_movk_i32 s83, 1024
	s_mov_b32 s84, -1
	s_mul_i32 s85, s79, 10485760
	s_add_u32 s86, s64, s85
	s_addc_u32 s87, s65, 0
	s_mul_i32 s85, s79, 5242880
	s_add_u32 s88, s74, s85
	s_addc_u32 s89, s75, 0
	s_branch .Ltr_p5bs1_dec_done

; #define LAUNDER(v) asm volatile("" : "+s"(v))
; __device__ __forceinline__ int vtid() { int t = threadIdx.x; asm volatile("" : "+v"(t)); return t; }
; __device__ __forceinline__ unsigned pack2(float a, float b) { return (unsigned)f2bf(a) | ((unsigned)f2bf(b) << 16); }
; __device__ __forceinline__ void tr_store(const Params& p, char* ws, int job, int tid, const float* tile) {
;   TrJob t = tr_decode(p, ws, job);
;   const int kc = tid & 7, nn = tid >> 3;
; #pragma unroll
;   for (int pp = 0; pp < 2; ++pp) {
;     int n = nn + 32 * pp;
;     float v[8];
; #pragma unroll
;     for (int j = 0; j < 8; ++j) v[j] = tile[(kc * 8 + j) * 65 + n];
;     uint4 o;
;     o.x = pack2(v[0], v[1]); o.y = pack2(v[2], v[3]); o.z = pack2(v[4], v[5]); o.w = pack2(v[6], v[7]);
;     int gn = t.nt * 64 + n;
;     int drow = t.mode == 0 ? gn : gu_row(t.mode - 1, gn);
;     *(uint4*)&t.dst[(size_t)drow * t.K + t.kt * 64 + kc * 8] = o;
;   }
; }
; __device__ __forceinline__ void p0_transposes(const Params& p, char* smem, int bid, int nb, int jlo, int jhi) {
;   const int tid = vtid();
;   char* ws = p.ws;
;   LAUNDER(ws);
;   float* tileA = (float*)smem;
;   float* tileB = tileA + 64 * 65;
;   float4 c0[4], c1[4], n0[4], n1[4];
;   int j = jlo + bid * 2;
;   if (j < jhi) { tr_load(p, ws, j, tid, c0); tr_load(p, ws, j + 1, tid, c1); }
;   for (; j < jhi; j += 2 * nb) {
;     const int jn = j + 2 * nb;
;     if (jn < jhi) { tr_load(p, ws, jn, tid, n0); tr_load(p, ws, jn + 1, tid, n1); }
;     tr_lds_write(tileA, tid, c0);
;     tr_lds_write(tileB, tid, c1);
;     __syncthreads();
;     tr_store(p, ws, j, tid, tileA);
;     tr_store(p, ws, j + 1, tid, tileB);
;     __syncthreads();
; #pragma unroll
;     for (int q = 0; q < 4; ++q) { c0[q] = n0[q]; c1[q] = n1[q]; }
;   }
.Ltr_p5bs1_dec_done:
	s_lshl_b32 s97, s83, 1
	s_cmp_eq_u32 s84, -1
	s_cselect_b32 s79, 6, 7
	s_cselect_b32 s85, 32, 64
	s_cselect_b32 s78, 0, s84
	s_lshl_b32 s79, s81, s79
	s_add_u32 s79, s79, s78
	s_add_u32 s85, s85, s79
	s_mul_i32 s79, s79, s97
	s_mul_i32 s85, s85, s97
	s_lshl_b32 s78, s80, 7
	s_add_u32 s79, s79, s78
	s_add_u32 s85, s85, s78
	s_add_u32 s94, s88, s79
	s_addc_u32 s95, s89, 0
	s_add_u32 s98, s88, s85
	s_addc_u32 s99, s89, 0
	v_mad_u32_u24 v254, v245, s97, v246
	s_movk_i32 s78, 0x7fff
	s_mov_b32 s79, 0xffff0000
	s_waitcnt lgkmcnt(0)
	v_bfe_u32 v252, v228, 16, 1
	v_bfe_u32 v253, v229, 16, 1
	v_add3_u32 v252, v228, v252, s78
	v_add3_u32 v253, v229, v253, s78
	v_lshrrev_b32_e32 v252, 16, v252
	v_and_or_b32 v248, v253, s79, v252
	v_bfe_u32 v252, v230, 16, 1
	v_bfe_u32 v253, v231, 16, 1
	v_add3_u32 v252, v230, v252, s78
	v_add3_u32 v253, v231, v253, s78
	v_lshrrev_b32_e32 v252, 16, v252
	v_and_or_b32 v249, v253, s79, v252
	v_bfe_u32 v252, v232, 16, 1
	v_bfe_u32 v253, v233, 16, 1
	v_add3_u32 v252, v232, v252, s78
	v_add3_u32 v253, v233, v253, s78
	v_lshrrev_b32_e32 v252, 16, v252
	v_and_or_b32 v250, v253, s79, v252
	v_bfe_u32 v252, v234, 16, 1
	v_bfe_u32 v253, v235, 16, 1
	v_add3_u32 v252, v234, v252, s78
	v_add3_u32 v253, v235, v253, s78
	v_lshrrev_b32_e32 v252, 16, v252
	v_and_or_b32 v251, v253, s79, v252
	global_store_dwordx4 v254, v[248:251], s[94:95]
	s_nop 1
	v_bfe_u32 v252, v186, 16, 1
	v_bfe_u32 v253, v187, 16, 1
	v_add3_u32 v252, v186, v252, s78
	v_add3_u32 v253, v187, v253, s78
	v_lshrrev_b32_e32 v252, 16, v252
	v_and_or_b32 v248, v253, s79, v252
	v_bfe_u32 v252, v188, 16, 1
	v_bfe_u32 v253, v189, 16, 1
	v_add3_u32 v252, v188, v252, s78
	v_add3_u32 v253, v189, v253, s78
	v_lshrrev_b32_e32 v252, 16, v252
	v_and_or_b32 v249, v253, s79, v252
	v_bfe_u32 v252, v190, 16, 1
	v_bfe_u32 v253, v191, 16, 1
	v_add3_u32 v252, v190, v252, s78
	v_add3_u32 v253, v191, v253, s78
	v_lshrrev_b32_e32 v252, 16, v252
	v_and_or_b32 v250, v253, s79, v252
	v_bfe_u32 v252, v192, 16, 1
	v_bfe_u32 v253, v193, 16, 1
	v_add3_u32 v252, v192, v252, s78
	v_add3_u32 v253, v193, v253, s78
	v_lshrrev_b32_e32 v252, 16, v252
	v_and_or_b32 v251, v253, s79, v252
	global_store_dwordx4 v254, v[248:251], s[98:99]
	s_xor_b32 s96, s96, 0x4100
	s_add_u32 s76, s76, 480
	s_sub_u32 s77, s77, 1
	s_cmp_lg_u32 s77, 0
	s_cbranch_scc1 .Ltrp5b_batch
	s_waitcnt vmcnt(0) lgkmcnt(0)
	s_barrier
	v_readlane_b32 s64, v255, 0
	v_readlane_b32 s65, v255, 1
	v_readlane_b32 s66, v255, 2
	v_readlane_b32 s67, v255, 3
	v_readlane_b32 s68, v255, 4
	v_readlane_b32 s69, v255, 5
	v_readlane_b32 s70, v255, 6
	v_readlane_b32 s71, v255, 7
	v_readlane_b32 s72, v255, 8
	v_readlane_b32 s73, v255, 9
	v_readlane_b32 s74, v255, 10
	v_readlane_b32 s75, v255, 11
	v_readlane_b32 s76, v255, 12
	v_readlane_b32 s77, v255, 13
	v_readlane_b32 s78, v255, 14
	v_readlane_b32 s79, v255, 15
	v_readlane_b32 s80, v255, 16
	v_readlane_b32 s81, v255, 17
	v_readlane_b32 s82, v255, 18
	v_readlane_b32 s83, v255, 19
	v_readlane_b32 s84, v255, 20
	v_readlane_b32 s85, v255, 21
	v_readlane_b32 s86, v255, 22
	v_readlane_b32 s87, v255, 23
	v_readlane_b32 s88, v255, 24
	v_readlane_b32 s89, v255, 25
	v_readlane_b32 s90, v255, 26
	v_readlane_b32 s91, v255, 27
	v_readlane_b32 s92, v255, 28
	v_readlane_b32 s93, v255, 29
	v_readlane_b32 s94, v255, 30
	v_readlane_b32 s95, v255, 31
	v_readlane_b32 s96, v255, 32
	v_readlane_b32 s97, v255, 33
	v_readlane_b32 s98, v255, 34
	v_readlane_b32 s99, v255, 35
	v_readlane_b32 vcc_lo, v255, 36
	v_readlane_b32 vcc_hi, v255, 37
	s_nop 4
